# K-loop tail: MFMA blocks padded to the same 4-mod-8 byte parity as the main loop (on top of v87)
# baseline (speedup 1.0000x reference)
; #define PG8_LDA(dst, b, h) do { _Pragma("unroll") for (int m = 0; m < 4; ++m) _Pragma("unroll") for (int k = 0; k < 2; ++k) dst[m][k] = *(const LAS bf16x8*)(lds + PG8_SA(b, h) + aoff + m * 2048 + k * 1024); } while (0)
; #define PG8_LDB(dst, b, h) do { _Pragma("unroll") for (int n = 0; n < 2; ++n) _Pragma("unroll") for (int k = 0; k < 2; ++k) dst[n][k] = *(const LAS bf16x8*)(lds + PG8_SB(b, h) + boff + n * 2048 + k * 1024); } while (0)
; #define PG8_MMA(ai, bj, At, Bt) do { __builtin_amdgcn_s_setprio(1); _Pragma("unroll") for (int m = 0; m < 4; ++m) _Pragma("unroll") for (int n = 0; n < 2; ++n) _Pragma("unroll") for (int k = 0; k < 2; ++k) \
;         acc[ai][bj][m][n] = __builtin_amdgcn_mfma_f32_16x16x32_bf16(Bt[n][k], At[m][k], acc[ai][bj][m][n], 0, 0, 0); __builtin_amdgcn_s_setprio(0); } while (0)
; #define PG8_WAIT_V(n) asm volatile("s_waitcnt vmcnt(" #n ")" ::: "memory")
; #define PG8_WAIT_L(n) asm volatile("s_waitcnt lgkmcnt(" #n ")" ::: "memory")
; #define PG8_BAR __builtin_amdgcn_s_barrier()
; #define PG8_SCHED __builtin_amdgcn_sched_barrier(0)
; #define PG8_STA(bufoff, gbase, ld) PG8_STAGE(bufoff, gbase, RA0 * (unsigned)(ld) + CC0, RA1 * (unsigned)(ld) + CC1)
; __device__ __forceinline__ void gemm_phase(LAS unsigned char* lds, const Sched& S, const Epi& E) {
;     ...
;             const char* a1 = cA + (size_t)(nt - 1) * kstep;
;             PG8_LDB(B0, 0, 0); PG8_LDB(B1, 0, 1); PG8_SCHED; PG8_LDA(At, 0, 0); PG8_STA(PG8_SA(1, 1), a1 + hA, lda);
;             PG8_WAIT_V(8); PG8_WAIT_L(0); PG8_BAR; PG8_MMA(0, 0, At, B0); PG8_MMA(0, 1, At, B1); PG8_BAR; PG8_SCHED;
;             PG8_LDA(At, 0, 1);
;             PG8_WAIT_V(2); PG8_WAIT_L(0); PG8_BAR; PG8_MMA(1, 0, At, B0); PG8_MMA(1, 1, At, B1); PG8_BAR; PG8_SCHED;
.LBB0_265:
	v_add_u32_e32 v0, 0, v241
	v_add_u32_e32 v142, 0x10000, v0
	v_add_u32_e32 v158, 0x14000, v0
	s_waitcnt lgkmcnt(0)
	ds_read_b128 v[130:133], v142
	ds_read_b128 v[134:137], v142 offset:1024
	ds_read_b128 v[138:141], v142 offset:2048
	ds_read_b128 v[142:145], v142 offset:3072
	ds_read_b128 v[146:149], v158
	ds_read_b128 v[150:153], v158 offset:1024
	ds_read_b128 v[154:157], v158 offset:2048
	ds_read_b128 v[158:161], v158 offset:3072
	s_ashr_i32 s61, s60, 31
	s_lshl_b64 s[8:9], s[60:61], 7
	s_add_u32 s2, s96, s8
	s_addc_u32 s8, s97, s9
	s_add_u32 s2, s2, s66
	s_addc_u32 s9, s8, s67
	s_add_u32 s8, s2, 0xffffff80
	v_add_u32_e32 v212, 0, v240
	s_addc_u32 s9, s9, -1
	v_mad_u64_u32 v[210:211], s[26:27], s20, v235, v[194:195]
	s_add_i32 m0, s34, 0xc000
	ds_read_b128 v[162:165], v212
	ds_read_b128 v[166:169], v212 offset:1024
	ds_read_b128 v[170:173], v212 offset:2048
	ds_read_b128 v[174:177], v212 offset:3072
	ds_read_b128 v[178:181], v212 offset:4096
	ds_read_b128 v[182:185], v212 offset:5120
	ds_read_b128 v[186:189], v212 offset:6144
	ds_read_b128 v[190:193], v212 offset:7168
	global_load_lds_dwordx4 v210, s[8:9]
	v_mad_u64_u32 v[210:211], s[20:21], s20, v236, v[196:197]
	s_add_i32 m0, s34, 0xe000
	s_nop 0
	global_load_lds_dwordx4 v210, s[8:9]
	s_waitcnt vmcnt(8)
	s_waitcnt lgkmcnt(0)
	s_barrier
	s_setprio 1
	s_waitcnt lgkmcnt(0)
	s_nop 0
	v_mfma_f32_16x16x32_bf16 v[126:129], v[130:133], v[162:165], v[126:129]
	v_mfma_f32_16x16x32_bf16 v[122:125], v[138:141], v[162:165], v[122:125]
	v_mfma_f32_16x16x32_bf16 v[110:113], v[130:133], v[170:173], v[110:113]
	v_mfma_f32_16x16x32_bf16 v[106:109], v[138:141], v[170:173], v[106:109]
	v_mfma_f32_16x16x32_bf16 v[98:101], v[130:133], v[178:181], v[98:101]
	v_mfma_f32_16x16x32_bf16 v[90:93], v[138:141], v[178:181], v[90:93]
	v_mfma_f32_16x16x32_bf16 v[82:85], v[130:133], v[186:189], v[82:85]
	v_mfma_f32_16x16x32_bf16 v[74:77], v[138:141], v[186:189], v[74:77]
	v_mfma_f32_16x16x32_bf16 v[126:129], v[134:137], v[166:169], v[126:129]
	v_mfma_f32_16x16x32_bf16 v[122:125], v[142:145], v[166:169], v[122:125]
	v_mfma_f32_16x16x32_bf16 v[110:113], v[134:137], v[174:177], v[110:113]
	v_mfma_f32_16x16x32_bf16 v[106:109], v[142:145], v[174:177], v[106:109]
	v_mfma_f32_16x16x32_bf16 v[98:101], v[134:137], v[182:185], v[98:101]
	v_mfma_f32_16x16x32_bf16 v[90:93], v[142:145], v[182:185], v[90:93]
	v_mfma_f32_16x16x32_bf16 v[82:85], v[134:137], v[190:193], v[82:85]
	v_mfma_f32_16x16x32_bf16 v[74:77], v[142:145], v[190:193], v[74:77]
	s_setprio 0
	s_setprio 1
	v_mfma_f32_16x16x32_bf16 v[118:121], v[146:149], v[162:165], v[118:121]
	v_mfma_f32_16x16x32_bf16 v[114:117], v[154:157], v[162:165], v[114:117]
	v_mfma_f32_16x16x32_bf16 v[102:105], v[146:149], v[170:173], v[102:105]
	v_mfma_f32_16x16x32_bf16 v[94:97], v[154:157], v[170:173], v[94:97]
	v_mfma_f32_16x16x32_bf16 v[86:89], v[146:149], v[178:181], v[86:89]
	v_mfma_f32_16x16x32_bf16 v[78:81], v[154:157], v[178:181], v[78:81]
	v_mfma_f32_16x16x32_bf16 v[70:73], v[146:149], v[186:189], v[70:73]
	v_mfma_f32_16x16x32_bf16 v[66:69], v[154:157], v[186:189], v[66:69]
	v_mfma_f32_16x16x32_bf16 v[118:121], v[150:153], v[166:169], v[118:121]
	v_mfma_f32_16x16x32_bf16 v[114:117], v[158:161], v[166:169], v[114:117]
	v_mfma_f32_16x16x32_bf16 v[102:105], v[150:153], v[174:177], v[102:105]
	v_mfma_f32_16x16x32_bf16 v[94:97], v[158:161], v[174:177], v[94:97]
	v_mfma_f32_16x16x32_bf16 v[86:89], v[150:153], v[182:185], v[86:89]
	v_mfma_f32_16x16x32_bf16 v[78:81], v[158:161], v[182:185], v[78:81]
	v_mfma_f32_16x16x32_bf16 v[70:73], v[150:153], v[190:193], v[70:73]
	v_mfma_f32_16x16x32_bf16 v[66:69], v[158:161], v[190:193], v[66:69]
	s_setprio 0
	s_barrier
	ds_read_b128 v[162:165], v212 offset:16384
	ds_read_b128 v[166:169], v212 offset:17408
	ds_read_b128 v[170:173], v212 offset:18432
	ds_read_b128 v[174:177], v212 offset:19456
	ds_read_b128 v[178:181], v212 offset:20480
	ds_read_b128 v[182:185], v212 offset:21504
	ds_read_b128 v[186:189], v212 offset:22528
	ds_read_b128 v[190:193], v212 offset:23552
	s_waitcnt vmcnt(2)
	s_waitcnt lgkmcnt(0)
	s_barrier
	s_setprio 1
	s_waitcnt lgkmcnt(0)
	s_nop 0
	v_mfma_f32_16x16x32_bf16 v[62:65], v[130:133], v[162:165], v[62:65]
	v_mfma_f32_16x16x32_bf16 v[58:61], v[138:141], v[162:165], v[58:61]
	v_mfma_f32_16x16x32_bf16 v[46:49], v[130:133], v[170:173], v[46:49]
	v_mfma_f32_16x16x32_bf16 v[42:45], v[138:141], v[170:173], v[42:45]
	v_mfma_f32_16x16x32_bf16 v[30:33], v[130:133], v[178:181], v[30:33]
	v_mfma_f32_16x16x32_bf16 v[26:29], v[138:141], v[178:181], v[26:29]
	v_mfma_f32_16x16x32_bf16 v[14:17], v[130:133], v[186:189], v[14:17]
	v_mfma_f32_16x16x32_bf16 v[10:13], v[138:141], v[186:189], v[10:13]
	v_mfma_f32_16x16x32_bf16 v[62:65], v[134:137], v[166:169], v[62:65]
	v_mfma_f32_16x16x32_bf16 v[58:61], v[142:145], v[166:169], v[58:61]
	v_mfma_f32_16x16x32_bf16 v[46:49], v[134:137], v[174:177], v[46:49]
	v_mfma_f32_16x16x32_bf16 v[42:45], v[142:145], v[174:177], v[42:45]
	v_mfma_f32_16x16x32_bf16 v[30:33], v[134:137], v[182:185], v[30:33]
	v_mfma_f32_16x16x32_bf16 v[26:29], v[142:145], v[182:185], v[26:29]
	v_mfma_f32_16x16x32_bf16 v[14:17], v[134:137], v[190:193], v[14:17]
	v_mfma_f32_16x16x32_bf16 v[10:13], v[142:145], v[190:193], v[10:13]
	s_setprio 0
	s_setprio 1
	v_mfma_f32_16x16x32_bf16 v[54:57], v[146:149], v[162:165], v[54:57]
	v_mfma_f32_16x16x32_bf16 v[50:53], v[154:157], v[162:165], v[50:53]
	v_mfma_f32_16x16x32_bf16 v[38:41], v[146:149], v[170:173], v[38:41]
	v_mfma_f32_16x16x32_bf16 v[34:37], v[154:157], v[170:173], v[34:37]
	v_mfma_f32_16x16x32_bf16 v[22:25], v[146:149], v[178:181], v[22:25]
	v_mfma_f32_16x16x32_bf16 v[18:21], v[154:157], v[178:181], v[18:21]
	v_mfma_f32_16x16x32_bf16 v[6:9], v[146:149], v[186:189], v[6:9]
	v_mfma_f32_16x16x32_bf16 v[2:5], v[154:157], v[186:189], v[2:5]
	v_mfma_f32_16x16x32_bf16 v[54:57], v[150:153], v[166:169], v[54:57]
	v_mfma_f32_16x16x32_bf16 v[50:53], v[158:161], v[166:169], v[50:53]
	v_mfma_f32_16x16x32_bf16 v[38:41], v[150:153], v[174:177], v[38:41]
	v_mfma_f32_16x16x32_bf16 v[34:37], v[158:161], v[174:177], v[34:37]
	v_mfma_f32_16x16x32_bf16 v[22:25], v[150:153], v[182:185], v[22:25]
	v_mfma_f32_16x16x32_bf16 v[18:21], v[158:161], v[182:185], v[18:21]
	v_mfma_f32_16x16x32_bf16 v[6:9], v[150:153], v[190:193], v[6:9]
	v_mfma_f32_16x16x32_bf16 v[2:5], v[158:161], v[190:193], v[2:5]
	s_setprio 0
	s_barrier
; #define PG8_LDA(dst, b, h) do { _Pragma("unroll") for (int m = 0; m < 4; ++m) _Pragma("unroll") for (int k = 0; k < 2; ++k) dst[m][k] = *(const LAS bf16x8*)(lds + PG8_SA(b, h) + aoff + m * 2048 + k * 1024); } while (0)
; #define PG8_LDB(dst, b, h) do { _Pragma("unroll") for (int n = 0; n < 2; ++n) _Pragma("unroll") for (int k = 0; k < 2; ++k) dst[n][k] = *(const LAS bf16x8*)(lds + PG8_SB(b, h) + boff + n * 2048 + k * 1024); } while (0)
; #define PG8_MMA(ai, bj, At, Bt) do { __builtin_amdgcn_s_setprio(1); _Pragma("unroll") for (int m = 0; m < 4; ++m) _Pragma("unroll") for (int n = 0; n < 2; ++n) _Pragma("unroll") for (int k = 0; k < 2; ++k) \
;         acc[ai][bj][m][n] = __builtin_amdgcn_mfma_f32_16x16x32_bf16(Bt[n][k], At[m][k], acc[ai][bj][m][n], 0, 0, 0); __builtin_amdgcn_s_setprio(0); } while (0)
; #define PG8_WAIT_V(n) asm volatile("s_waitcnt vmcnt(" #n ")" ::: "memory")
; #define PG8_WAIT_L(n) asm volatile("s_waitcnt lgkmcnt(" #n ")" ::: "memory")
; #define PG8_BAR __builtin_amdgcn_s_barrier()
; #define PG8_SCHED __builtin_amdgcn_sched_barrier(0)
; __device__ __forceinline__ void gemm_phase(LAS unsigned char* lds, const Sched& S, const Epi& E) {
;     ...
;             PG8_LDB(B0, 1, 0); PG8_LDB(B1, 1, 1); PG8_SCHED; PG8_LDA(At, 1, 0);
;             PG8_WAIT_V(0); PG8_WAIT_L(0); PG8_BAR; PG8_MMA(0, 0, At, B0); PG8_MMA(0, 1, At, B1); PG8_BAR; PG8_SCHED;
;             PG8_LDA(At, 1, 1);
;             PG8_WAIT_L(0); PG8_BAR; PG8_MMA(1, 0, At, B0); PG8_MMA(1, 1, At, B1); PG8_BAR; PG8_SCHED;
	v_add_u32_e32 v142, 0x18000, v0
	v_add_u32_e32 v0, 0x1c000, v0
	ds_read_b128 v[130:133], v142
	ds_read_b128 v[134:137], v142 offset:1024
	ds_read_b128 v[138:141], v142 offset:2048
	ds_read_b128 v[142:145], v142 offset:3072
	ds_read_b128 v[146:149], v0
	ds_read_b128 v[150:153], v0 offset:1024
	ds_read_b128 v[154:157], v0 offset:2048
	ds_read_b128 v[158:161], v0 offset:3072
	ds_read_b128 v[162:165], v212 offset:32768
	ds_read_b128 v[166:169], v212 offset:33792
	ds_read_b128 v[170:173], v212 offset:34816
	ds_read_b128 v[174:177], v212 offset:35840
	ds_read_b128 v[178:181], v212 offset:36864
	ds_read_b128 v[182:185], v212 offset:37888
	ds_read_b128 v[186:189], v212 offset:38912
	ds_read_b128 v[190:193], v212 offset:39936
	s_waitcnt vmcnt(0)
	s_waitcnt lgkmcnt(0)
	s_barrier
	s_setprio 1
	s_waitcnt lgkmcnt(0)
	s_nop 0
	v_mfma_f32_16x16x32_bf16 v[126:129], v[130:133], v[162:165], v[126:129]
	v_mfma_f32_16x16x32_bf16 v[122:125], v[138:141], v[162:165], v[122:125]
	v_mfma_f32_16x16x32_bf16 v[110:113], v[130:133], v[170:173], v[110:113]
	v_mfma_f32_16x16x32_bf16 v[106:109], v[138:141], v[170:173], v[106:109]
	v_mfma_f32_16x16x32_bf16 v[98:101], v[130:133], v[178:181], v[98:101]
	v_mfma_f32_16x16x32_bf16 v[90:93], v[138:141], v[178:181], v[90:93]
	v_mfma_f32_16x16x32_bf16 v[82:85], v[130:133], v[186:189], v[82:85]
	v_mfma_f32_16x16x32_bf16 v[74:77], v[138:141], v[186:189], v[74:77]
	v_mfma_f32_16x16x32_bf16 v[126:129], v[134:137], v[166:169], v[126:129]
	v_mfma_f32_16x16x32_bf16 v[122:125], v[142:145], v[166:169], v[122:125]
	v_mfma_f32_16x16x32_bf16 v[110:113], v[134:137], v[174:177], v[110:113]
	v_mfma_f32_16x16x32_bf16 v[106:109], v[142:145], v[174:177], v[106:109]
	v_mfma_f32_16x16x32_bf16 v[98:101], v[134:137], v[182:185], v[98:101]
	v_mfma_f32_16x16x32_bf16 v[90:93], v[142:145], v[182:185], v[90:93]
	v_mfma_f32_16x16x32_bf16 v[82:85], v[134:137], v[190:193], v[82:85]
	v_mfma_f32_16x16x32_bf16 v[74:77], v[142:145], v[190:193], v[74:77]
	s_setprio 0
	s_setprio 1
	v_mfma_f32_16x16x32_bf16 v[118:121], v[146:149], v[162:165], v[118:121]
	v_mfma_f32_16x16x32_bf16 v[114:117], v[154:157], v[162:165], v[114:117]
	v_mfma_f32_16x16x32_bf16 v[102:105], v[146:149], v[170:173], v[102:105]
	v_mfma_f32_16x16x32_bf16 v[94:97], v[154:157], v[170:173], v[94:97]
	v_mfma_f32_16x16x32_bf16 v[86:89], v[146:149], v[178:181], v[86:89]
	v_mfma_f32_16x16x32_bf16 v[78:81], v[154:157], v[178:181], v[78:81]
	v_mfma_f32_16x16x32_bf16 v[70:73], v[146:149], v[186:189], v[70:73]
	v_mfma_f32_16x16x32_bf16 v[66:69], v[154:157], v[186:189], v[66:69]
	v_mfma_f32_16x16x32_bf16 v[118:121], v[150:153], v[166:169], v[118:121]
	v_mfma_f32_16x16x32_bf16 v[114:117], v[158:161], v[166:169], v[114:117]
	v_mfma_f32_16x16x32_bf16 v[102:105], v[150:153], v[174:177], v[102:105]
	v_mfma_f32_16x16x32_bf16 v[94:97], v[158:161], v[174:177], v[94:97]
	v_mfma_f32_16x16x32_bf16 v[86:89], v[150:153], v[182:185], v[86:89]
	v_mfma_f32_16x16x32_bf16 v[78:81], v[158:161], v[182:185], v[78:81]
	v_mfma_f32_16x16x32_bf16 v[70:73], v[150:153], v[190:193], v[70:73]
	v_mfma_f32_16x16x32_bf16 v[66:69], v[158:161], v[190:193], v[66:69]
	s_setprio 0
	s_barrier
	ds_read_b128 v[162:165], v212 offset:49152
	ds_read_b128 v[166:169], v212 offset:50176
	ds_read_b128 v[170:173], v212 offset:51200
	ds_read_b128 v[174:177], v212 offset:52224
	ds_read_b128 v[178:181], v212 offset:53248
	ds_read_b128 v[182:185], v212 offset:54272
	ds_read_b128 v[186:189], v212 offset:55296
	ds_read_b128 v[190:193], v212 offset:56320
	s_waitcnt lgkmcnt(0)
	s_barrier
	s_setprio 1
	s_waitcnt lgkmcnt(0)
	v_mfma_f32_16x16x32_bf16 v[62:65], v[130:133], v[162:165], v[62:65]
	v_mfma_f32_16x16x32_bf16 v[58:61], v[138:141], v[162:165], v[58:61]
	v_mfma_f32_16x16x32_bf16 v[46:49], v[130:133], v[170:173], v[46:49]
	v_mfma_f32_16x16x32_bf16 v[42:45], v[138:141], v[170:173], v[42:45]
	v_mfma_f32_16x16x32_bf16 v[30:33], v[130:133], v[178:181], v[30:33]
	v_mfma_f32_16x16x32_bf16 v[26:29], v[138:141], v[178:181], v[26:29]
	v_mfma_f32_16x16x32_bf16 v[14:17], v[130:133], v[186:189], v[14:17]
	v_mfma_f32_16x16x32_bf16 v[10:13], v[138:141], v[186:189], v[10:13]
	v_mfma_f32_16x16x32_bf16 v[62:65], v[134:137], v[166:169], v[62:65]
	v_mfma_f32_16x16x32_bf16 v[58:61], v[142:145], v[166:169], v[58:61]
	v_mfma_f32_16x16x32_bf16 v[46:49], v[134:137], v[174:177], v[46:49]
	v_mfma_f32_16x16x32_bf16 v[42:45], v[142:145], v[174:177], v[42:45]
	v_mfma_f32_16x16x32_bf16 v[30:33], v[134:137], v[182:185], v[30:33]
	v_mfma_f32_16x16x32_bf16 v[26:29], v[142:145], v[182:185], v[26:29]
	v_mfma_f32_16x16x32_bf16 v[14:17], v[134:137], v[190:193], v[14:17]
	v_mfma_f32_16x16x32_bf16 v[10:13], v[142:145], v[190:193], v[10:13]
	s_setprio 0
	s_setprio 1
	v_mfma_f32_16x16x32_bf16 v[54:57], v[146:149], v[162:165], v[54:57]
	v_mfma_f32_16x16x32_bf16 v[50:53], v[154:157], v[162:165], v[50:53]
	v_mfma_f32_16x16x32_bf16 v[38:41], v[146:149], v[170:173], v[38:41]
	v_mfma_f32_16x16x32_bf16 v[34:37], v[154:157], v[170:173], v[34:37]
	v_mfma_f32_16x16x32_bf16 v[22:25], v[146:149], v[178:181], v[22:25]
	v_mfma_f32_16x16x32_bf16 v[18:21], v[154:157], v[178:181], v[18:21]
	v_mfma_f32_16x16x32_bf16 v[6:9], v[146:149], v[186:189], v[6:9]
	v_mfma_f32_16x16x32_bf16 v[2:5], v[154:157], v[186:189], v[2:5]
	v_mfma_f32_16x16x32_bf16 v[54:57], v[150:153], v[166:169], v[54:57]
	v_mfma_f32_16x16x32_bf16 v[50:53], v[158:161], v[166:169], v[50:53]
	v_mfma_f32_16x16x32_bf16 v[38:41], v[150:153], v[174:177], v[38:41]
	v_mfma_f32_16x16x32_bf16 v[34:37], v[158:161], v[174:177], v[34:37]
	v_mfma_f32_16x16x32_bf16 v[22:25], v[150:153], v[182:185], v[22:25]
	v_mfma_f32_16x16x32_bf16 v[18:21], v[158:161], v[182:185], v[18:21]
	v_mfma_f32_16x16x32_bf16 v[6:9], v[150:153], v[190:193], v[6:9]
	v_mfma_f32_16x16x32_bf16 v[2:5], v[158:161], v[190:193], v[2:5]
	s_setprio 0
	s_barrier
	s_nop 0
